# v8 + next-layer w_up conversion items 27000..31999 moved from the prologue into the FFN-up phase slot (idle workgroups)
# speedup vs baseline: 1.0076x; 1.0006x over previous
; #define GAS __attribute__((address_space(1)))
; #define LAS __attribute__((address_space(3)))
; __device__ __forceinline__ const GAS float* inp(const Ctx& c, int k) { return (const GAS float*)ptab(c, k); }
; #define PRB(id) _Pragma("nounroll") for (int r_ = 0; r_ < ((id) == PROBE_ID ? PROBE_N : 1); ++r_)
; template <int DEP> __device__ __forceinline__ void conv_items(const Ctx& c0, int l, int b0, int b1, int wIdx, int nW) { const Ctx c = fresh(c0);
;     ...
;     { const int t4 = c.tid * 4; f32x4 gi = (f32x4){1.f, 1.f, 1.f, 1.f}, bi = (f32x4){0.f, 0.f, 0.f, 0.f};
;       if (l > 0) { gi = *(const GAS f32x4*)(inp(c, 33) + (size_t)(l - 1) * D + t4); bi = *(const GAS f32x4*)(inp(c, 34) + (size_t)(l - 1) * D + t4); }
;       const f32x4 gu = *(const GAS f32x4*)(inp(c, 28) + (size_t)l * D + t4), bu = *(const GAS f32x4*)(inp(c, 29) + (size_t)l * D + t4);
;       *(LAS f32x4*)(GB + t4) = gi; *(LAS f32x4*)(GB + 2048 + t4) = bi; *(LAS f32x4*)(GB + 4096 + t4) = gu; *(LAS f32x4*)(GB + 6144 + t4) = bu; }
;     __syncthreads();
;     const int lane = c.lane, kr = lane >> 3, ns = lane & 7;
;     int it = b0 + wIdx;
;     if (it >= b1) return;
; __device__ __forceinline__ void prologue(const Ctx& c0) { const Ctx c = fresh(c0);
;     ...
;     PRB(900) for (int l = 0; l < DEPTH; ++l) { const int p0 = (DEFER_CONV && l > 0) ? CONV_B3 : 0; if (p0 < CONV_TOT) conv_items<1>(c, l, p0, CONV_TOT, c.gw, c.NGW); }
.LBB0_663:
	v_mov_b32_e32 v11, 0x22600
	s_waitcnt vmcnt(6)
	ds_read2_b32 v[12:13], v11 offset0:56 offset1:57
	s_and_b64 s[0:1], s[0:1], exec
	s_mov_b32 s7, s3
	s_cselect_b32 s2, 0, 0x7d00
	s_lshl_b64 s[0:1], s[6:7], 13
	s_waitcnt lgkmcnt(0)
	v_readfirstlane_b32 s8, v12
	v_readfirstlane_b32 s9, v13
	s_add_u32 s8, s8, s0
	s_addc_u32 s9, s9, s1
	s_waitcnt vmcnt(4)
	v_lshlrev_b64 v[16:17], 2, v[8:9]
	v_lshl_add_u64 v[12:13], s[8:9], 0, v[16:17]
	v_mov_b32_e32 v9, 0x22600
	global_load_dwordx4 v[12:15], v[12:13], off
	ds_read2_b32 v[18:19], v9 offset0:58 offset1:59
	v_lshlrev_b32_e32 v8, 2, v8
	v_add_u32_e32 v9, 0x11400, v8
	v_add_u32_e32 v20, 0x15400, v8
	v_add_u32_e32 v11, 0x13400, v8
	s_waitcnt lgkmcnt(0)
	v_readfirstlane_b32 s7, v18
	v_readfirstlane_b32 s8, v19
	s_add_u32 s0, s7, s0
	s_addc_u32 s1, s8, s1
	v_lshl_add_u64 v[16:17], s[0:1], 0, v[16:17]
	global_load_dwordx4 v[16:19], v[16:17], off
	s_add_i32 s35, s2, s41
	s_cmp_gt_i32 s35, 0x92ff
	v_add_u32_e32 v8, 0x17400, v8
	s_waitcnt vmcnt(3)
	ds_write_b128 v9, v[0:3]
	s_waitcnt vmcnt(2)
	ds_write_b128 v11, v[4:7]
	s_waitcnt vmcnt(1)
	ds_write_b128 v20, v[12:15]
	s_waitcnt vmcnt(0)
	ds_write_b128 v8, v[16:19]
	s_waitcnt lgkmcnt(0)
	s_barrier
	s_cbranch_scc1 .LBB0_658
	s_cmpk_gt_i32 s35, 0x38ff
	s_mov_b64 s[10:11], -1
	s_cbranch_scc0 .LBB0_699
	s_cmpk_gt_u32 s35, 0x40ff
	s_cbranch_scc0 .LBB0_682
	s_cmpk_gt_u32 s35, 0x44ff
	s_cbranch_scc0 .LBB0_679
	s_cmpk_gt_u32 s35, 0x48ff
	s_cbranch_scc0 .LBB0_676
	s_cmpk_gt_u32 s35, 0x50ff
	s_cbranch_scc0 .LBB0_673
	s_cmpk_gt_u32 s35, 0x7cff
	s_mov_b64 s[0:1], -1
	s_cbranch_scc0 .LBB0_671
	s_add_i32 s0, s35, 0xffff8300
	s_lshr_b32 s13, s0, 6
	s_and_b32 s7, s35, 63
	s_mov_b64 s[0:1], 0

; #define GAS __attribute__((address_space(1)))
; #define LAS __attribute__((address_space(3)))
; __device__ __forceinline__ const GAS float* inp(const Ctx& c, int k) { return (const GAS float*)ptab(c, k); }
; template <int DEP> __device__ __forceinline__ void conv_items(const Ctx& c0, int l, int b0, int b1, int wIdx, int nW) { const Ctx c = fresh(c0);
;     ...
;     { const int t4 = c.tid * 4; f32x4 gi = (f32x4){1.f, 1.f, 1.f, 1.f}, bi = (f32x4){0.f, 0.f, 0.f, 0.f};
;       if (l > 0) { gi = *(const GAS f32x4*)(inp(c, 33) + (size_t)(l - 1) * D + t4); bi = *(const GAS f32x4*)(inp(c, 34) + (size_t)(l - 1) * D + t4); }
;       const f32x4 gu = *(const GAS f32x4*)(inp(c, 28) + (size_t)l * D + t4), bu = *(const GAS f32x4*)(inp(c, 29) + (size_t)l * D + t4);
;       *(LAS f32x4*)(GB + t4) = gi; *(LAS f32x4*)(GB + 2048 + t4) = bi; *(LAS f32x4*)(GB + 4096 + t4) = gu; *(LAS f32x4*)(GB + 6144 + t4) = bu; }
;     __syncthreads();
;     const int lane = c.lane, kr = lane >> 3, ns = lane & 7;
;     int it = b0 + wIdx;
;     if (it >= b1) return;
.LBB0_2940:
	v_mov_b32_e32 v12, 0x22600
	ds_read2_b32 v[12:13], v12 offset0:56 offset1:57
	v_readlane_b32 s0, v254, 55
	s_sub_i32 s0, s34, s0
	s_lshl_b32 s12, s0, 3
	s_add_i32 s0, s76, 1
	s_ashr_i32 s1, s0, 31
	s_add_i32 s12, s12, s95
	s_waitcnt lgkmcnt(0)
	v_readfirstlane_b32 s6, v12
	s_lshl_b64 s[2:3], s[0:1], 13
	v_readfirstlane_b32 s7, v13
	s_add_u32 s6, s6, s2
	s_addc_u32 s7, s7, s3
	v_lshlrev_b64 v[16:17], 2, v[10:11]
	v_lshl_add_u64 v[12:13], s[6:7], 0, v[16:17]
	v_mov_b32_e32 v11, 0x22600
	global_load_dwordx4 v[12:15], v[12:13], off
	ds_read2_b32 v[18:19], v11 offset0:58 offset1:59
	v_lshlrev_b32_e32 v10, 2, v10
	v_add_u32_e32 v11, 0x11400, v10
	s_waitcnt vmcnt(2)
	ds_write_b128 v11, v[6:9]
	v_add_u32_e32 v6, 0x13400, v10
	s_waitcnt lgkmcnt(1)
	v_readfirstlane_b32 s6, v18
	v_readfirstlane_b32 s7, v19
	s_add_u32 s2, s6, s2
	s_addc_u32 s3, s7, s3
	v_lshl_add_u64 v[16:17], s[2:3], 0, v[16:17]
	global_load_dwordx4 v[16:19], v[16:17], off
	s_waitcnt vmcnt(2)
	ds_write_b128 v6, v[2:5]
	v_add_u32_e32 v2, 0x15400, v10
	s_cmpk_gt_i32 s12, 0x32c7
	s_waitcnt vmcnt(1)
	ds_write_b128 v2, v[12:15]
	v_add_u32_e32 v2, 0x17400, v10
	s_waitcnt vmcnt(0)
	ds_write_b128 v2, v[16:19]
	s_waitcnt lgkmcnt(0)
	s_barrier
	s_cbranch_scc1 .LBB0_3623
	s_add_i32 s40, s12, 0x4a38
	s_cmpk_gt_i32 s12, 0xeec7
	s_mov_b64 s[8:9], -1
	s_cbranch_scc0 .LBB0_2972
	s_cmpk_gt_u32 s40, 0x40ff
	s_cbranch_scc0 .LBB0_2955
	s_cmpk_gt_u32 s40, 0x44ff
	s_cbranch_scc0 .LBB0_2952
	s_cmpk_gt_u32 s40, 0x48ff
	s_mov_b64 s[6:7], -1
	s_cbranch_scc0 .LBB0_2949
	s_cmpk_gt_u32 s40, 0x50ff
	s_mov_b64 s[2:3], -1
	s_cbranch_scc0 .LBB0_2947
	s_add_i32 s2, s12, 0xfffff938
	s_mul_i32 s3, s2, 0xba2f
	s_lshr_b32 s11, s3, 24
	s_mul_i32 s3, s11, 0xfffffea0
	s_add_i32 s10, s3, s2
	s_mov_b64 s[2:3], 0

; #define TR_LOAD(dst, item_) do { int item = (item_); item = item < last ? item : last; const ConvItem d_ = conv_decode(item); const GAS float* src_ = conv_src(c, l, d_) + (size_t)(64 * d_.kb + kr) * d_.N + 32 * d_.nb + 4 * ns; \
;         _Pragma("unroll") for (int i = 0; i < 8; ++i) dst[i] = __builtin_nontemporal_load((const GAS f32x4*)(src_ + (size_t)(8 * i) * d_.N)); } while (0)
; template <int DEP> __device__ __forceinline__ void conv_items(const Ctx& c0, int l, int b0, int b1, int wIdx, int nW) { const Ctx c = fresh(c0);
;     ...
;         TR_LOAD(q0, it); TR_LOAD(q1, it + nW); TR_LOAD(q2, it + 2 * nW);
; #pragma nounroll
;         for (;;) {
;             TR_LOAD(q3, it + 3 * nW); TR_PROC(q0, it); it += nW; if (it >= b1) break;
;             TR_LOAD(q0, it + 3 * nW); TR_PROC(q1, it); it += nW; if (it >= b1) break;
;             TR_LOAD(q1, it + 3 * nW); TR_PROC(q2, it); it += nW; if (it >= b1) break;
;             TR_LOAD(q2, it + 3 * nW); TR_PROC(q3, it); it += nW; if (it >= b1) break;
.LBB0_2977:
	v_mov_b32_e32 v2, 0x22600
	s_mul_i32 s8, s2, s1
	v_add_u32_e32 v2, s13, v2
	s_mul_hi_u32 s13, s2, s0
	ds_read2_b32 v[2:3], v2 offset1:1
	s_add_i32 s8, s13, s8
	s_mul_i32 s13, s3, s0
	s_add_i32 s8, s8, s13
	s_mul_i32 s13, s2, s0
	s_mul_i32 s7, s13, s7
	s_mul_hi_u32 s14, s13, s6
	v_ashrrev_i32_e32 v132, 3, v0
	s_add_i32 s7, s14, s7
	s_mul_i32 s8, s8, s6
	v_and_b32_e32 v98, 7, v0
	s_add_i32 s7, s7, s8
	s_mul_i32 s6, s13, s6
	v_lshl_add_u32 v0, s11, 6, v132
	s_waitcnt lgkmcnt(0)
	v_readfirstlane_b32 s9, v2
	s_lshl_b64 s[6:7], s[6:7], 2
	v_ashrrev_i32_e32 v2, 31, v0
	v_readfirstlane_b32 s12, v3
	s_add_u32 s6, s9, s6
	v_mul_lo_u32 v4, s2, v2
	v_mul_lo_u32 v5, s3, v0
	v_mad_u64_u32 v[2:3], s[8:9], s2, v0, 0
	s_addc_u32 s7, s12, s7
	v_add3_u32 v3, v3, v4, v5
	v_lshl_add_u64 v[2:3], v[2:3], 2, s[6:7]
	s_lshl_b32 s6, s10, 5
	s_ashr_i32 s7, s6, 31
	v_lshl_add_u64 v[2:3], s[6:7], 2, v[2:3]
	v_lshlrev_b32_e32 v0, 4, v98
	v_lshl_add_u64 v[2:3], v[2:3], 0, v[0:1]
	s_lshl_b64 s[2:3], s[2:3], 5
	v_lshl_add_u64 v[10:11], v[2:3], 0, s[2:3]
	global_load_dwordx4 v[2:5], v[2:3], off nt
	s_nop 0
	global_load_dwordx4 v[6:9], v[10:11], off nt
	v_lshl_add_u64 v[10:11], v[10:11], 0, s[2:3]
	v_lshl_add_u64 v[18:19], v[10:11], 0, s[2:3]
	global_load_dwordx4 v[10:13], v[10:11], off nt
	s_nop 0
	global_load_dwordx4 v[14:17], v[18:19], off nt
	v_lshl_add_u64 v[18:19], v[18:19], 0, s[2:3]
	v_lshl_add_u64 v[22:23], v[18:19], 0, s[2:3]
	global_load_dwordx4 v[18:21], v[18:19], off nt
	s_nop 0
	global_load_dwordx4 v[30:33], v[22:23], off nt
	v_lshl_add_u64 v[22:23], v[22:23], 0, s[2:3]
	global_load_dwordx4 v[26:29], v[22:23], off nt
	v_lshl_add_u64 v[22:23], v[22:23], 0, s[2:3]
	global_load_dwordx4 v[22:25], v[22:23], off nt
	v_readlane_b32 s2, v254, 14
	s_add_i32 s10, s40, s2
	s_min_i32 s15, s10, 0x7cff
	s_cmpk_gt_i32 s10, 0x38ff
	s_mov_b64 s[8:9], -1
	s_cbranch_scc0 .LBB0_3008
	s_cmpk_gt_u32 s10, 0x40ff
	s_cbranch_scc0 .LBB0_2991
	s_cmpk_gt_u32 s10, 0x44ff
	s_cbranch_scc0 .LBB0_2988
	s_cmpk_gt_u32 s10, 0x48ff
	s_mov_b64 s[6:7], -1
	s_cbranch_scc0 .LBB0_2985
	s_cmpk_gt_u32 s10, 0x50ff
	s_mov_b64 s[2:3], -1
	s_cbranch_scc0 .LBB0_2983
	s_add_i32 s2, s15, 0xffffaf00
	s_mul_i32 s3, s2, 0xba2f
	s_lshr_b32 s12, s3, 24
	s_mul_i32 s3, s12, 0xfffffea0
	s_add_i32 s11, s3, s2
	s_mov_b64 s[2:3], 0

; #define TR_LOAD(dst, item_) do { int item = (item_); item = item < last ? item : last; const ConvItem d_ = conv_decode(item); const GAS float* src_ = conv_src(c, l, d_) + (size_t)(64 * d_.kb + kr) * d_.N + 32 * d_.nb + 4 * ns; \
;         _Pragma("unroll") for (int i = 0; i < 8; ++i) dst[i] = __builtin_nontemporal_load((const GAS f32x4*)(src_ + (size_t)(8 * i) * d_.N)); } while (0)
; template <int DEP> __device__ __forceinline__ void conv_items(const Ctx& c0, int l, int b0, int b1, int wIdx, int nW) { const Ctx c = fresh(c0);
;     ...
;         TR_LOAD(q0, it); TR_LOAD(q1, it + nW); TR_LOAD(q2, it + 2 * nW);
; #pragma nounroll
;         for (;;) {
;             TR_LOAD(q3, it + 3 * nW); TR_PROC(q0, it); it += nW; if (it >= b1) break;
;             TR_LOAD(q0, it + 3 * nW); TR_PROC(q1, it); it += nW; if (it >= b1) break;
;             TR_LOAD(q1, it + 3 * nW); TR_PROC(q2, it); it += nW; if (it >= b1) break;
;             TR_LOAD(q2, it + 3 * nW); TR_PROC(q3, it); it += nW; if (it >= b1) break;
.LBB0_3013:
	v_mov_b32_e32 v34, 0x22600
	s_mul_i32 s8, s2, s1
	v_add_u32_e32 v34, s13, v34
	ds_read2_b32 v[34:35], v34 offset1:1
	s_mul_hi_u32 s9, s2, s0
	s_add_i32 s8, s9, s8
	s_mul_i32 s14, s3, s0
	s_add_i32 s8, s8, s14
	s_mul_i32 s14, s2, s0
	s_mul_i32 s7, s14, s7
	s_mul_hi_u32 s15, s14, s6
	s_add_i32 s7, s15, s7
	s_mul_i32 s8, s8, s6
	s_waitcnt lgkmcnt(0)
	v_readfirstlane_b32 s9, v34
	s_add_i32 s7, s7, s8
	s_mul_i32 s6, s14, s6
	v_lshl_add_u32 v34, s12, 6, v132
	v_readfirstlane_b32 s13, v35
	s_lshl_b64 s[6:7], s[6:7], 2
	v_ashrrev_i32_e32 v35, 31, v34
	s_add_u32 s6, s9, s6
	v_mul_lo_u32 v36, s2, v35
	v_mul_lo_u32 v37, s3, v34
	v_mad_u64_u32 v[34:35], s[8:9], s2, v34, 0
	s_addc_u32 s7, s13, s7
	v_add3_u32 v35, v35, v36, v37
	v_lshl_add_u64 v[34:35], v[34:35], 2, s[6:7]
	s_lshl_b32 s6, s11, 5
	s_ashr_i32 s7, s6, 31
	v_lshl_add_u64 v[34:35], s[6:7], 2, v[34:35]
	v_lshlrev_b32_e32 v0, 2, v0
	v_lshl_add_u64 v[34:35], v[34:35], 0, v[0:1]
	s_lshl_b64 s[2:3], s[2:3], 5
	v_lshl_add_u64 v[42:43], v[34:35], 0, s[2:3]
	global_load_dwordx4 v[34:37], v[34:35], off nt
	s_nop 0
	global_load_dwordx4 v[38:41], v[42:43], off nt
	v_lshl_add_u64 v[42:43], v[42:43], 0, s[2:3]
	v_lshl_add_u64 v[50:51], v[42:43], 0, s[2:3]
	global_load_dwordx4 v[42:45], v[42:43], off nt
	s_nop 0
	global_load_dwordx4 v[46:49], v[50:51], off nt
	v_lshl_add_u64 v[50:51], v[50:51], 0, s[2:3]
	v_lshl_add_u64 v[58:59], v[50:51], 0, s[2:3]
	v_lshl_add_u64 v[62:63], v[58:59], 0, s[2:3]
	global_load_dwordx4 v[50:53], v[50:51], off nt
	s_nop 0
	global_load_dwordx4 v[54:57], v[58:59], off nt
	s_mov_b64 s[8:9], -1
	global_load_dwordx4 v[58:61], v[62:63], off nt
	v_lshl_add_u64 v[62:63], v[62:63], 0, s[2:3]
	global_load_dwordx4 v[62:65], v[62:63], off nt
	v_readlane_b32 s2, v254, 14
	s_add_i32 s15, s10, s2
	s_min_i32 s14, s15, 0x7cff
	s_cmpk_gt_i32 s15, 0x38ff
	s_cbranch_scc0 .LBB0_3044
	s_cmpk_gt_u32 s15, 0x40ff
	s_cbranch_scc0 .LBB0_3027
	s_cmpk_gt_u32 s15, 0x44ff
	s_cbranch_scc0 .LBB0_3024
	s_cmpk_gt_u32 s15, 0x48ff
	s_mov_b64 s[6:7], -1
	s_cbranch_scc0 .LBB0_3021
	s_cmpk_gt_u32 s15, 0x50ff
	s_mov_b64 s[2:3], -1
	s_cbranch_scc0 .LBB0_3019
	s_add_i32 s2, s14, 0xffffaf00
	s_mul_i32 s3, s2, 0xba2f
	s_lshr_b32 s11, s3, 24
	s_mul_i32 s3, s11, 0xfffffea0
	s_add_i32 s10, s3, s2
	s_mov_b64 s[2:3], 0

; #define TR_LOAD(dst, item_) do { int item = (item_); item = item < last ? item : last; const ConvItem d_ = conv_decode(item); const GAS float* src_ = conv_src(c, l, d_) + (size_t)(64 * d_.kb + kr) * d_.N + 32 * d_.nb + 4 * ns; \
;         _Pragma("unroll") for (int i = 0; i < 8; ++i) dst[i] = __builtin_nontemporal_load((const GAS f32x4*)(src_ + (size_t)(8 * i) * d_.N)); } while (0)
; template <int DEP> __device__ __forceinline__ void conv_items(const Ctx& c0, int l, int b0, int b1, int wIdx, int nW) { const Ctx c = fresh(c0);
;     ...
;         for (;;) {
;             TR_LOAD(q3, it + 3 * nW); TR_PROC(q0, it); it += nW; if (it >= b1) break;
;             TR_LOAD(q0, it + 3 * nW); TR_PROC(q1, it); it += nW; if (it >= b1) break;
;             TR_LOAD(q1, it + 3 * nW); TR_PROC(q2, it); it += nW; if (it >= b1) break;
;             TR_LOAD(q2, it + 3 * nW); TR_PROC(q3, it); it += nW; if (it >= b1) break;
.LBB0_3051:
	v_readlane_b32 s8, v254, 14
	s_add_i32 s40, s5, s8
	v_readlane_b32 s8, v254, 41
	s_add_i32 s36, s36, s8
	s_waitcnt lgkmcnt(0)
	s_add_i32 s5, s20, s36
	s_add_i32 s37, s37, s8
	s_add_i32 s21, s21, s8
	s_addk_i32 s5, 0x4a38
	s_add_i32 s35, s35, s8
	s_add_i32 s22, s22, s8
	s_add_i32 s34, s34, s8
	s_add_i32 s31, s31, s8
	s_add_i32 s30, s30, s8
	s_add_i32 s23, s23, s8
	s_add_i32 s29, s29, s8
	s_add_i32 s28, s28, s8
	s_add_i32 s27, s27, s8
	s_add_i32 s24, s24, s8
	s_add_i32 s26, s26, s8
	s_add_i32 s25, s25, s8
	s_cmpk_gt_i32 s5, 0x7cff
	s_cselect_b64 s[10:11], -1, 0

; #define TR_LOAD(dst, item_) do { int item = (item_); item = item < last ? item : last; const ConvItem d_ = conv_decode(item); const GAS float* src_ = conv_src(c, l, d_) + (size_t)(64 * d_.kb + kr) * d_.N + 32 * d_.nb + 4 * ns; \
;         _Pragma("unroll") for (int i = 0; i < 8; ++i) dst[i] = __builtin_nontemporal_load((const GAS f32x4*)(src_ + (size_t)(8 * i) * d_.N)); } while (0)
; template <int DEP> __device__ __forceinline__ void conv_items(const Ctx& c0, int l, int b0, int b1, int wIdx, int nW) { const Ctx c = fresh(c0);
;     ...
;             TR_LOAD(q3, it + 3 * nW); TR_PROC(q0, it); it += nW; if (it >= b1) break;
;             TR_LOAD(q0, it + 3 * nW); TR_PROC(q1, it); it += nW; if (it >= b1) break;
;             TR_LOAD(q1, it + 3 * nW); TR_PROC(q2, it); it += nW; if (it >= b1) break;
;             TR_LOAD(q2, it + 3 * nW); TR_PROC(q3, it); it += nW; if (it >= b1) break;
.LBB0_3053:
	s_add_i32 s39, s20, s26
	s_add_i32 s38, s39, 0x4a38
	s_min_i32 s19, s38, 0x7cff
	s_cmpk_gt_i32 s38, 0x38ff
	s_cselect_b64 s[8:9], -1, 0
	s_mov_b64 s[14:15], -1
	s_and_b64 vcc, exec, s[8:9]
	s_cbranch_vccz .LBB0_3084
	s_cmpk_gt_u32 s38, 0x40ff
	s_cbranch_scc0 .LBB0_3067
	s_cmpk_gt_u32 s38, 0x44ff
	s_cbranch_scc0 .LBB0_3064
	s_cmpk_gt_u32 s38, 0x48ff
	s_mov_b64 s[12:13], -1
	s_cbranch_scc0 .LBB0_3061
	s_cmpk_gt_u32 s38, 0x50ff
	s_mov_b64 s[10:11], -1
	s_cbranch_scc0 .LBB0_3059
	s_add_i32 s5, s19, 0xffffaf00
	s_mul_i32 s10, s5, 0xba2f
	s_lshr_b32 s16, s10, 24
	s_mul_i32 s10, s16, 0xfffffea0
	s_add_i32 s5, s10, s5
	s_mov_b64 s[10:11], 0

; #define TR_LOAD(dst, item_) do { int item = (item_); item = item < last ? item : last; const ConvItem d_ = conv_decode(item); const GAS float* src_ = conv_src(c, l, d_) + (size_t)(64 * d_.kb + kr) * d_.N + 32 * d_.nb + 4 * ns; \
;         _Pragma("unroll") for (int i = 0; i < 8; ++i) dst[i] = __builtin_nontemporal_load((const GAS f32x4*)(src_ + (size_t)(8 * i) * d_.N)); } while (0)
; template <int DEP> __device__ __forceinline__ void conv_items(const Ctx& c0, int l, int b0, int b1, int wIdx, int nW) { const Ctx c = fresh(c0);
;     ...
;             TR_LOAD(q3, it + 3 * nW); TR_PROC(q0, it); it += nW; if (it >= b1) break;
;             TR_LOAD(q0, it + 3 * nW); TR_PROC(q1, it); it += nW; if (it >= b1) break;
;             TR_LOAD(q1, it + 3 * nW); TR_PROC(q2, it); it += nW; if (it >= b1) break;
;             TR_LOAD(q2, it + 3 * nW); TR_PROC(q3, it); it += nW; if (it >= b1) break;
.LBB0_3193:
	s_waitcnt lgkmcnt(0)
	s_add_i32 s5, s20, s34
	s_add_i32 s18, s5, 0x4a38
	s_cmpk_gt_i32 s18, 0x7cff
	s_mov_b64 s[10:11], -1
	s_cbranch_scc1 .LBB0_3052
	s_add_i32 s42, s20, s31
	s_min_i32 s41, s42, 0x7cff
	s_cmpk_gt_i32 s42, 0x38ff
	s_mov_b64 s[14:15], -1
	s_cbranch_scc0 .LBB0_3225
	s_cmpk_gt_u32 s42, 0x40ff
	s_cbranch_scc0 .LBB0_3208
	s_cmpk_gt_u32 s42, 0x44ff
	s_cbranch_scc0 .LBB0_3205
	s_cmpk_gt_u32 s42, 0x48ff
	s_mov_b64 s[12:13], -1
	s_cbranch_scc0 .LBB0_3202
	s_cmpk_gt_u32 s42, 0x50ff
	s_mov_b64 s[10:11], -1
	s_cbranch_scc0 .LBB0_3200
	s_add_i32 s10, s41, 0xffffaf00
	s_mul_i32 s11, s10, 0xba2f
	s_lshr_b32 s17, s11, 24
	s_mul_i32 s11, s17, 0xfffffea0
	s_add_i32 s16, s11, s10
	s_mov_b64 s[10:11], 0

; #define TR_LOAD(dst, item_) do { int item = (item_); item = item < last ? item : last; const ConvItem d_ = conv_decode(item); const GAS float* src_ = conv_src(c, l, d_) + (size_t)(64 * d_.kb + kr) * d_.N + 32 * d_.nb + 4 * ns; \
;         _Pragma("unroll") for (int i = 0; i < 8; ++i) dst[i] = __builtin_nontemporal_load((const GAS f32x4*)(src_ + (size_t)(8 * i) * d_.N)); } while (0)
; template <int DEP> __device__ __forceinline__ void conv_items(const Ctx& c0, int l, int b0, int b1, int wIdx, int nW) { const Ctx c = fresh(c0);
;     ...
;             TR_LOAD(q3, it + 3 * nW); TR_PROC(q0, it); it += nW; if (it >= b1) break;
;             TR_LOAD(q0, it + 3 * nW); TR_PROC(q1, it); it += nW; if (it >= b1) break;
;             TR_LOAD(q1, it + 3 * nW); TR_PROC(q2, it); it += nW; if (it >= b1) break;
;             TR_LOAD(q2, it + 3 * nW); TR_PROC(q3, it); it += nW; if (it >= b1) break;
.LBB0_3334:
	s_waitcnt lgkmcnt(0)
	s_add_i32 s19, s20, s29
	s_add_i32 s18, s19, 0x4a38
	s_cmpk_gt_i32 s18, 0x7cff
	s_mov_b64 s[10:11], -1
	s_cbranch_scc1 .LBB0_3052
	s_add_i32 s42, s20, s28
	s_min_i32 s41, s42, 0x7cff
	s_cmpk_gt_i32 s42, 0x38ff
	s_mov_b64 s[14:15], -1
	s_cbranch_scc0 .LBB0_3366
	s_cmpk_gt_u32 s42, 0x40ff
	s_cbranch_scc0 .LBB0_3349
	s_cmpk_gt_u32 s42, 0x44ff
	s_cbranch_scc0 .LBB0_3346
	s_cmpk_gt_u32 s42, 0x48ff
	s_mov_b64 s[12:13], -1
	s_cbranch_scc0 .LBB0_3343
	s_cmpk_gt_u32 s42, 0x50ff
	s_mov_b64 s[10:11], -1
	s_cbranch_scc0 .LBB0_3341
	s_add_i32 s10, s41, 0xffffaf00
	s_mul_i32 s11, s10, 0xba2f
	s_lshr_b32 s17, s11, 24
	s_mul_i32 s11, s17, 0xfffffea0
	s_add_i32 s16, s11, s10
	s_mov_b64 s[10:11], 0

; #define TR_LOAD(dst, item_) do { int item = (item_); item = item < last ? item : last; const ConvItem d_ = conv_decode(item); const GAS float* src_ = conv_src(c, l, d_) + (size_t)(64 * d_.kb + kr) * d_.N + 32 * d_.nb + 4 * ns; \
;         _Pragma("unroll") for (int i = 0; i < 8; ++i) dst[i] = __builtin_nontemporal_load((const GAS f32x4*)(src_ + (size_t)(8 * i) * d_.N)); } while (0)
; template <int DEP> __device__ __forceinline__ void conv_items(const Ctx& c0, int l, int b0, int b1, int wIdx, int nW) { const Ctx c = fresh(c0);
;     ...
;             TR_LOAD(q3, it + 3 * nW); TR_PROC(q0, it); it += nW; if (it >= b1) break;
;             TR_LOAD(q0, it + 3 * nW); TR_PROC(q1, it); it += nW; if (it >= b1) break;
;             TR_LOAD(q1, it + 3 * nW); TR_PROC(q2, it); it += nW; if (it >= b1) break;
;             TR_LOAD(q2, it + 3 * nW); TR_PROC(q3, it); it += nW; if (it >= b1) break;
.LBB0_3477:
	s_waitcnt lgkmcnt(0)
	s_cmpk_gt_i32 s38, 0x7cff
	s_mov_b64 s[10:11], -1
	s_cbranch_scc1 .LBB0_3052
	s_add_i32 s40, s20, s25
	s_min_i32 s33, s40, 0x7cff
	s_cmpk_gt_i32 s40, 0x38ff
	s_mov_b64 s[14:15], -1
	s_cbranch_scc0 .LBB0_3509
	s_cmpk_gt_u32 s40, 0x40ff
	s_cbranch_scc0 .LBB0_3492
	s_cmpk_gt_u32 s40, 0x44ff
	s_cbranch_scc0 .LBB0_3489
	s_cmpk_gt_u32 s40, 0x48ff
	s_mov_b64 s[12:13], -1
	s_cbranch_scc0 .LBB0_3486
	s_cmpk_gt_u32 s40, 0x50ff
	s_mov_b64 s[10:11], -1
	s_cbranch_scc0 .LBB0_3484
	s_add_i32 s10, s33, 0xffffaf00
	s_mul_i32 s11, s10, 0xba2f
	s_lshr_b32 s17, s11, 24
	s_mul_i32 s11, s17, 0xfffffea0
	s_add_i32 s16, s11, s10
	s_mov_b64 s[10:11], 0
